# MoBA spread prefetch: K addresses from a per-item 64-bit base + scalar offsets (10 fewer VALU and 11 fewer nops per computing wave-step)
# speedup vs baseline: 1.0119x; 1.0043x over previous
.LBB0_93:
	s_xor_b64 s[56:57], s[0:1], -1
	s_and_b64 s[0:1], s[0:1], exec
	s_cselect_b32 s8, s43, s44
	s_lshl_b32 s46, s8, 7
	s_ashr_i32 s1, s46, 31
	s_add_u32 s0, s46, s6
	s_addc_u32 s1, s1, 0
	v_lshl_add_u64 v[36:37], s[0:1], 0, v[116:117]
	v_mov_b64_e32 v[40:41], s[88:89]
	v_mad_u64_u32 v[38:39], s[10:11], v36, s72, v[40:41]
	v_mad_i32_i24 v39, v37, s72, v39
	s_lshl_b32 s20, s45, 1
	v_mov_b64_e32 v[250:251], s[88:89]
	v_mad_u64_u32 v[250:251], s[82:83], v140, s72, v[250:251]
	v_mad_i32_i24 v251, v141, s72, v251
	v_lshl_add_u64 v[250:251], v[250:251], 0, s[20:21]
	v_lshl_add_u64 v[250:251], v[250:251], 0, v[2:3]
	v_lshl_add_u64 v[36:37], v[38:39], 0, s[20:21]
	v_lshl_add_u64 v[36:37], v[36:37], 0, v[2:3]
	v_add_co_u32_e32 v36, vcc, s3, v36
	s_nop 1
	v_addc_co_u32_e32 v37, vcc, 0, v37, vcc
	global_load_dwordx4 v[4:7], v[36:37], off
	v_lshl_add_u64 v[36:37], s[0:1], 0, v[122:123]
	v_mad_u64_u32 v[38:39], s[10:11], v36, s72, v[40:41]
	v_mad_i32_i24 v39, v37, s72, v39
	v_lshl_add_u64 v[36:37], v[38:39], 0, s[20:21]
	v_lshl_add_u64 v[36:37], v[36:37], 0, v[2:3]
	v_add_co_u32_e32 v36, vcc, s3, v36
	s_nop 1
	v_addc_co_u32_e32 v37, vcc, 0, v37, vcc
	global_load_dwordx4 v[8:11], v[36:37], off
	v_lshl_add_u64 v[36:37], s[0:1], 0, v[124:125]
	v_mad_u64_u32 v[38:39], s[10:11], v36, s72, v[40:41]
	v_mad_i32_i24 v39, v37, s72, v39
	v_lshl_add_u64 v[36:37], v[38:39], 0, s[20:21]
	v_lshl_add_u64 v[36:37], v[36:37], 0, v[2:3]
	v_add_co_u32_e32 v36, vcc, s3, v36
	s_nop 1
	v_addc_co_u32_e32 v37, vcc, 0, v37, vcc
	global_load_dwordx4 v[12:15], v[36:37], off
	v_lshl_add_u64 v[36:37], s[0:1], 0, v[126:127]
	v_mad_u64_u32 v[38:39], s[0:1], v36, s72, v[40:41]
	v_mad_i32_i24 v39, v37, s72, v39
	v_lshl_add_u64 v[36:37], v[38:39], 0, s[20:21]
	v_lshl_add_u64 v[36:37], v[36:37], 0, v[2:3]
	v_add_co_u32_e32 v36, vcc, 0x1000, v36
	s_nop 1
	v_addc_co_u32_e32 v37, vcc, 0, v37, vcc
	global_load_dwordx4 v[16:19], v[36:37], off
	v_lshrrev_b32_e32 v36, 5, v173
	v_lshlrev_b32_e32 v36, 9, v36
	v_mov_b32_e32 v37, 0
	v_lshl_add_u64 v[36:37], v[142:143], 0, v[36:37]
	global_load_dwordx4 v[20:23], v[36:37], off
	global_load_dwordx4 v[24:27], v[36:37], off offset:512
	s_barrier
	v_add_u32_e32 v52, v133, v170
	v_mov_b32_e32 v44, v156
	v_mov_b32_e32 v45, v135
	v_mov_b32_e32 v40, 0
	s_mov_b32 s0, 16
	v_mov_b32_e32 v41, v40
	v_mov_b32_e32 v42, v40
	v_mov_b32_e32 v43, v40
	s_waitcnt vmcnt(5)
	ds_write_b128 v52, v[4:7]
	s_waitcnt vmcnt(4)
	ds_write_b128 v188, v[8:11]
	s_waitcnt vmcnt(3)
	ds_write_b128 v189, v[12:15]
	s_waitcnt vmcnt(2)
	ds_write_b128 v190, v[16:19]
	s_waitcnt vmcnt(0)
	v_lshl_add_u32 v52, v173, 4, v171
	v_mov_b32_e32 v28, v20
	v_mov_b32_e32 v29, v24
	v_mov_b32_e32 v30, v21
	v_mov_b32_e32 v31, v25
	v_mov_b32_e32 v32, v22
	v_mov_b32_e32 v33, v26
	v_mov_b32_e32 v34, v23
	v_mov_b32_e32 v35, v27
	ds_write_b128 v52, v[28:31]
	ds_write_b128 v52, v[32:35] offset:16
	v_mov_b32_e32 v38, v40
	v_mov_b32_e32 v39, v40
	v_mov_b32_e32 v36, v40
	v_mov_b32_e32 v37, v40
	s_waitcnt lgkmcnt(0)
	s_barrier
	v_readfirstlane_b32 s82, v1
	s_ashr_i32 s83, s8, 1
	s_nop 3
	s_cmp_ge_i32 s82, s83
	s_cbranch_scc1 .Lgate_skip
	v_mov_b32_e32 v202, v45
	v_add_u32_e32 v203, 0x11000, v44
	ds_read_b128 v[4:7], v202
	ds_read_b128 v[8:11], v203
	ds_read_b128 v[12:15], v203 offset:16
	ds_read_b128 v[16:19], v203 offset:32
	ds_read_b128 v[20:23], v203 offset:48
	ds_read_b128 v[24:27], v203 offset:1024
	ds_read_b128 v[28:31], v203 offset:1040
	ds_read_b128 v[32:35], v203 offset:1056
	ds_read_b128 v[88:91], v203 offset:1072
	s_waitcnt lgkmcnt(7)
	ds_read_b128 v[92:95], v203 offset:2048
	ds_read_b128 v[96:99], v203 offset:2064
	ds_read_b128 v[100:103], v203 offset:2080
	ds_read_b128 v[104:107], v203 offset:2096
	ds_read_b128 v[108:111], v203 offset:3072
	ds_read_b128 v[112:115], v203 offset:3088
	ds_read_b128 v[194:197], v203 offset:3104
	ds_read_b128 v[198:201], v203 offset:3120

.Lms_inter:
	v_mov_b32_e32 v198, v197
	s_nop 1
	v_permlane16_swap_b32_e32 v197, v198
	v_max_f32_e32 v197, v197, v198
	v_mov_b32_e32 v198, v197
	s_nop 1
	v_permlane32_swap_b32_e32 v197, v198
	v_max3_f32 v197, v196, v197, v198
	v_cmp_neq_f32_e32 vcc, s73, v197
	s_nop 1
	v_cndmask_b32_e32 v198, 0, v197, vcc
	v_sub_f32_e32 v196, v196, v198
	v_mul_f32_e32 v199, 0x3e0293ee, v196
	v_mul_f32_e32 v196, 0xbe0293ee, v198
	v_cndmask_b32_e64 v198, v196, v215, s[0:1]
	v_fmamk_f32 v112, v112, 0x3e0293ee, v198
	v_exp_f32_e32 v112, v112
	s_xor_b32 s87, s15, 1
	v_fmamk_f32 v113, v113, 0x3e0293ee, v198
	v_exp_f32_e32 v113, v113
	s_mul_i32 s87, s87, 0x11000
	v_fmamk_f32 v114, v114, 0x3e0293ee, v198
	v_exp_f32_e32 v114, v114
	s_add_i32 s87, s87, 0
	v_fmamk_f32 v115, v115, 0x3e0293ee, v198
	v_exp_f32_e32 v115, v115
	v_add3_u32 v224, s87, v165, v216
	v_fmamk_f32 v108, v108, 0x3e0293ee, v198
	v_add3_u32 v223, s87, v0, v216
	v_add_f32_e32 v196, 0, v112
	v_exp_f32_e32 v108, v108
	v_add_u32_e32 v225, 0x8800, v224
	v_fmamk_f32 v109, v109, 0x3e0293ee, v198
	v_add_f32_e32 v196, v113, v196
	s_waitcnt vmcnt(7)
	v_exp_f32_e32 v109, v109
	v_fmamk_f32 v110, v110, 0x3e0293ee, v198
	ds_write_b128 v223, v[4:7]
	v_add_f32_e32 v196, v114, v196
	s_waitcnt vmcnt(6)
	v_exp_f32_e32 v110, v110
	v_fmamk_f32 v111, v111, 0x3e0293ee, v198
	ds_write2_b64 v225, v[8:9], v[10:11] offset1:2
	v_add_f32_e32 v196, v115, v196
	v_exp_f32_e32 v111, v111
	s_waitcnt vmcnt(5)
	v_fmamk_f32 v104, v104, 0x3e0293ee, v198
	v_add_f32_e32 v196, v108, v196
	ds_write_b128 v223, v[12:15] offset:8704
	v_exp_f32_e32 v104, v104
	v_add_u32_e32 v225, 0xa800, v224
	v_fmamk_f32 v105, v105, 0x3e0293ee, v198
	v_add_f32_e32 v196, v109, v196
	s_waitcnt vmcnt(4)
	v_exp_f32_e32 v105, v105
	v_fmamk_f32 v106, v106, 0x3e0293ee, v198
	ds_write2_b64 v225, v[16:17], v[18:19] offset0:64 offset1:66
	v_add_f32_e32 v196, v110, v196
	v_exp_f32_e32 v106, v106
	s_waitcnt vmcnt(3)
	v_fmamk_f32 v107, v107, 0x3e0293ee, v198
	ds_write_b128 v223, v[20:23] offset:17408
	v_add_f32_e32 v196, v111, v196
	v_exp_f32_e32 v107, v107
	v_add_u32_e32 v225, 0xc800, v224
	v_fmamk_f32 v100, v100, 0x3e0293ee, v198
	v_add_f32_e32 v196, v104, v196
	s_waitcnt vmcnt(2)
	v_exp_f32_e32 v100, v100
	v_fmamk_f32 v101, v101, 0x3e0293ee, v198
	ds_write2_b64 v225, v[24:25], v[26:27] offset0:128 offset1:130
	v_add_f32_e32 v196, v105, v196
	s_waitcnt vmcnt(1)
	v_exp_f32_e32 v101, v101
	v_fmamk_f32 v102, v102, 0x3e0293ee, v198
	ds_write_b128 v223, v[28:31] offset:26112
	v_add_f32_e32 v196, v106, v196
	v_exp_f32_e32 v102, v102
	v_add_u32_e32 v223, 0xe800, v224
	v_fmamk_f32 v103, v103, 0x3e0293ee, v198
	v_add_f32_e32 v196, v107, v196
	s_waitcnt vmcnt(0)
	v_exp_f32_e32 v103, v103
	ds_write2_b64 v223, v[32:33], v[34:35] offset0:192 offset1:194
	s_andn2_b64 vcc, exec, s[80:81]
	s_cbranch_vccnz .Lms_t2plain
	v_fmamk_f32 v96, v96, 0x3e0293ee, v198
	v_add_f32_e32 v196, v100, v196
	s_lshr_b32 s82, s14, 1
	v_exp_f32_e32 v96, v96
	v_fmamk_f32 v97, v97, 0x3e0293ee, v198
	s_sub_i32 s82, s47, s82
	v_add_f32_e32 v196, v101, v196
	v_exp_f32_e32 v97, v97
	s_lshl_b32 s83, s14, 7
	v_fmamk_f32 v98, v98, 0x3e0293ee, v198
	s_lshl_b32 s82, s82, 8
	v_add_f32_e32 v196, v102, v196
	v_exp_f32_e32 v98, v98
	s_and_b32 s83, s83, 0x80
	v_fmamk_f32 v99, v99, 0x3e0293ee, v198
	v_add_f32_e32 v196, v103, v196
	s_or_b32 s82, s82, s83
	v_exp_f32_e32 v99, v99
	v_fmamk_f32 v92, v92, 0x3e0293ee, v198
	s_ashr_i32 s83, s82, 31
	v_add_f32_e32 v196, v96, v196
	v_lshl_add_u64 v[28:29], s[82:83], 1, v[118:119]
	v_exp_f32_e32 v92, v92
	v_fmamk_f32 v93, v93, 0x3e0293ee, v198
	s_mul_i32 s82, s82, s72
	v_add_f32_e32 v196, v97, v196
	v_exp_f32_e32 v93, v93
	s_add_u32 s82, s82, s3
	v_fmamk_f32 v94, v94, 0x3e0293ee, v198
	v_add_f32_e32 v196, v98, v196
	s_mov_b32 s83, 0
	v_exp_f32_e32 v94, v94
	v_lshl_add_u64 v[4:5], v[250:251], 0, s[82:83]
	v_fmamk_f32 v95, v95, 0x3e0293ee, v198
	v_add_f32_e32 v196, v99, v196
	v_lshl_add_u64 v[8:9], v[28:29], 0, v[146:147]
	v_exp_f32_e32 v95, v95
	v_fmamk_f32 v88, v88, 0x3e0293ee, v198
	s_add_u32 s82, s82, 0x3c000
	v_add_f32_e32 v196, v92, v196
	v_lshl_add_u64 v[12:13], v[250:251], 0, s[82:83]
	v_exp_f32_e32 v88, v88
	v_fmamk_f32 v89, v89, 0x3e0293ee, v198
	v_lshl_add_u64 v[16:17], v[28:29], 0, v[148:149]
	v_add_f32_e32 v196, v93, v196
	v_exp_f32_e32 v89, v89
	s_add_u32 s82, s82, 0x3c000
	v_fmamk_f32 v90, v90, 0x3e0293ee, v198
	v_add_f32_e32 v196, v94, v196
	v_lshl_add_u64 v[20:21], v[250:251], 0, s[82:83]
	v_exp_f32_e32 v90, v90
	v_lshl_add_u64 v[24:25], v[28:29], 0, v[150:151]
	v_fmamk_f32 v91, v91, 0x3e0293ee, v198
	v_add_f32_e32 v196, v95, v196
	s_add_u32 s82, s82, 0x3c000
	v_exp_f32_e32 v91, v91
	v_add_f32_e32 v196, v88, v196
	v_lshl_add_u64 v[30:31], v[250:251], 0, s[82:83]
	v_add_f32_e32 v196, v89, v196
	v_add_f32_e32 v196, v90, v196
	v_lshl_add_u64 v[32:33], v[28:29], 0, v[152:153]
	v_fmamk_f32 v84, v84, 0x3e0293ee, v198
	global_load_dwordx4 v[4:7], v[4:5], off offset:1024
	v_add_f32_e32 v200, v91, v196
	v_exp_f32_e32 v196, v84
	global_load_dwordx4 v[8:11], v[8:9], off
	v_fmamk_f32 v85, v85, 0x3e0293ee, v198
	v_exp_f32_e32 v85, v85
	global_load_dwordx4 v[12:15], v[12:13], off offset:1024
	v_fmamk_f32 v86, v86, 0x3e0293ee, v198
	v_exp_f32_e32 v86, v86
	global_load_dwordx4 v[16:19], v[16:17], off
	v_fmac_f32_e32 v198, 0x3e0293ee, v87
	global_load_dwordx4 v[20:23], v[20:21], off offset:1024
	v_exp_f32_e32 v87, v198
	v_add_f32_e32 v84, v196, v200
	global_load_dwordx4 v[24:27], v[24:25], off
	v_add_f32_e32 v84, v85, v84
	v_add_f32_e32 v84, v86, v84
	global_load_dwordx4 v[28:31], v[30:31], off offset:1024
	v_add_f32_e32 v198, v87, v84
	global_load_dwordx4 v[32:35], v[32:33], off
	s_branch .Lms_join
